# plus A-fragment LDS reads software-pipelined into the preceding MFMA group in the O2 K-loop only
# baseline (speedup 1.0000x reference)
; #define PG8_STAGE_A(bufoff, ptr, half, rev) do { if (REVA && (rev)) { const char* _p = (ptr) - ((half) ? hstepA : 0); PG8_STAGE(bufoff, _p, voffAr); } else { const char* _p = (ptr) + ((half) ? hstepA : 0); PG8_STAGE(bufoff, _p, voffA); } } while (0)
; #define PG8_LDA(dst, b, h) do { _Pragma("unroll") for (int m = 0; m < 4; ++m) _Pragma("unroll") for (int k = 0; k < 2; ++k) dst[m][k] = *(const LAS bf16x8*)(lds + PG8_SA(b, h) + aoff + m * 2048 + k * 1024); } while (0)
; #define PG8_LDB(dst, b, h) do { _Pragma("unroll") for (int n = 0; n < 2; ++n) _Pragma("unroll") for (int k = 0; k < 2; ++k) dst[n][k] = *(const LAS bf16x8*)(lds + PG8_SB(b, h) + boff + n * 2048 + k * 1024); } while (0)
; #define PG8_WAIT_L(n) asm volatile("s_waitcnt lgkmcnt(" #n ")" ::: "memory")
; #define PG8_BAR __builtin_amdgcn_s_barrier()
; #define PG8_SCHED __builtin_amdgcn_sched_barrier(0)
;     ...
;     for (;;) {
;         const bool has_next = next_unit(ui + 1, nM, nN, MP, nxt, rot);
;         const char* nA = has_next ? nxt.a : cA; const char* nB = has_next ? nxt.b : cB; const char* nAr = has_next ? nxt.ar : cAr; const size_t nHb = has_next ? nxt.hb : cHb;
;         for (int t = 0; t < nt; t += 2) {
;             const bool last = (t == nt - 2);
;             const char* a1 = PG8_APTR(cA, cAr, t + 1); const bool r1 = REVA && ((t + 1) & 4);
;             const char* a2 = last ? nA : PG8_APTR(cA, cAr, t + 2); const bool r2 = REVA && !last && ((t + 2) & 4);
;             const char* a3 = last ? nA + kstep : PG8_APTR(cA, cAr, t + 3); const bool r3 = REVA && !last && ((t + 3) & 4);
;             const char* b2 = last ? nB : cB + (size_t)(t + 2) * kstep; const char* b3 = b2 + kstep; const size_t hb2 = last ? nHb : cHb;
;             PG8_LDB(B0, 0, 0); PG8_SCHED; PG8_LDA(At, 0, 0); PG8_STAGE_A(PG8_SA(1, 1), a1, 1, r1);
;             PG8_WAIT_L(8); PG8_BAR; PG8_WAIT_L(0); PG8_MMA(0, 0, At, B0); PG8_BAR; PG8_SCHED;
;     ...
; #pragma unroll
;         for (int a = 0; a < 2; ++a)
; #pragma unroll
;             for (int b = 0; b < 2; ++b)
; #pragma unroll
;                 for (int m = 0; m < 4; ++m)
; #pragma unroll
;                     for (int n = 0; n < 2; ++n) acc[a][b][m][n] = (f32x4){0.f, 0.f, 0.f, 0.f};
;         cur = nxt; cA = nA; cB = nB; cAr = nAr; cHb = nHb; ++ui;
.LBB0_233:
	s_add_u32 s3, s0, 0x80
	s_addc_u32 s6, s1, 0
	s_add_u32 s8, s38, 0x80080
	s_addc_u32 s9, s39, 0
	s_add_u32 s7, s20, 0x100
	v_mov_b32_e32 v0, 0
	v_lshl_add_u64 v[88:89], s[8:9], 0, v[150:151]
	v_lshl_add_u64 v[90:91], s[8:9], 0, v[152:153]
	s_addc_u32 s8, s21, 0
	s_mov_b32 s9, -2
	s_mov_b64 vcc, 0
	v_mov_b32_e32 v1, v0
	v_mov_b32_e32 v2, v0
	v_mov_b32_e32 v3, v0
	v_mov_b32_e32 v32, v0
	v_mov_b32_e32 v33, v0
	v_mov_b32_e32 v34, v0
	v_mov_b32_e32 v35, v0
	v_mov_b32_e32 v8, v0
	v_mov_b32_e32 v9, v0
	v_mov_b32_e32 v10, v0
	v_mov_b32_e32 v11, v0
	v_mov_b32_e32 v40, v0
	v_mov_b32_e32 v41, v0
	v_mov_b32_e32 v42, v0
	v_mov_b32_e32 v43, v0
	v_mov_b32_e32 v16, v0
	v_mov_b32_e32 v17, v0
	v_mov_b32_e32 v18, v0
	v_mov_b32_e32 v19, v0
	v_mov_b32_e32 v48, v0
	v_mov_b32_e32 v49, v0
	v_mov_b32_e32 v50, v0
	v_mov_b32_e32 v51, v0
	v_mov_b32_e32 v24, v0
	v_mov_b32_e32 v25, v0
	v_mov_b32_e32 v26, v0
	v_mov_b32_e32 v27, v0
	v_mov_b32_e32 v56, v0
	v_mov_b32_e32 v57, v0
	v_mov_b32_e32 v58, v0
	v_mov_b32_e32 v59, v0
	v_mov_b32_e32 v36, v0
	v_mov_b32_e32 v37, v0
	v_mov_b32_e32 v38, v0
	v_mov_b32_e32 v39, v0
	v_mov_b32_e32 v4, v0
	v_mov_b32_e32 v5, v0
	v_mov_b32_e32 v6, v0
	v_mov_b32_e32 v7, v0
	v_mov_b32_e32 v44, v0
	v_mov_b32_e32 v45, v0
	v_mov_b32_e32 v46, v0
	v_mov_b32_e32 v47, v0
	v_mov_b32_e32 v12, v0
	v_mov_b32_e32 v13, v0
	v_mov_b32_e32 v14, v0
	v_mov_b32_e32 v15, v0
	v_mov_b32_e32 v52, v0
	v_mov_b32_e32 v53, v0
	v_mov_b32_e32 v54, v0
	v_mov_b32_e32 v55, v0
	v_mov_b32_e32 v20, v0
	v_mov_b32_e32 v21, v0
	v_mov_b32_e32 v22, v0
	v_mov_b32_e32 v23, v0
	v_mov_b32_e32 v60, v0
	v_mov_b32_e32 v61, v0
	v_mov_b32_e32 v62, v0
	v_mov_b32_e32 v63, v0
	v_mov_b32_e32 v28, v0
	v_mov_b32_e32 v29, v0
	v_mov_b32_e32 v30, v0
	v_mov_b32_e32 v31, v0
	v_mov_b32_e32 v64, v0
	v_mov_b32_e32 v65, v0
	v_mov_b32_e32 v66, v0
	v_mov_b32_e32 v67, v0
	v_mov_b32_e32 v108, v0
	v_mov_b32_e32 v109, v0
	v_mov_b32_e32 v110, v0
	v_mov_b32_e32 v111, v0
	v_mov_b32_e32 v72, v0
	v_mov_b32_e32 v73, v0
	v_mov_b32_e32 v74, v0
	v_mov_b32_e32 v75, v0
	v_mov_b32_e32 v116, v0
	v_mov_b32_e32 v117, v0
	v_mov_b32_e32 v118, v0
	v_mov_b32_e32 v119, v0
	v_mov_b32_e32 v80, v0
	v_mov_b32_e32 v81, v0
	v_mov_b32_e32 v82, v0
	v_mov_b32_e32 v83, v0
	v_mov_b32_e32 v124, v0
	v_mov_b32_e32 v125, v0
	v_mov_b32_e32 v126, v0
	v_mov_b32_e32 v127, v0
	v_mov_b32_e32 v100, v0
	v_mov_b32_e32 v101, v0
	v_mov_b32_e32 v102, v0
	v_mov_b32_e32 v103, v0
	v_mov_b32_e32 v132, v0
	v_mov_b32_e32 v133, v0
	v_mov_b32_e32 v134, v0
	v_mov_b32_e32 v135, v0
	v_mov_b32_e32 v112, v0
	v_mov_b32_e32 v113, v0
	v_mov_b32_e32 v114, v0
	v_mov_b32_e32 v115, v0
	v_mov_b32_e32 v68, v0
	v_mov_b32_e32 v69, v0
	v_mov_b32_e32 v70, v0
	v_mov_b32_e32 v71, v0
	v_mov_b32_e32 v120, v0
	v_mov_b32_e32 v121, v0
	v_mov_b32_e32 v122, v0
	v_mov_b32_e32 v123, v0
	v_mov_b32_e32 v76, v0
	v_mov_b32_e32 v77, v0
	v_mov_b32_e32 v78, v0
	v_mov_b32_e32 v79, v0
	v_mov_b32_e32 v128, v0
	v_mov_b32_e32 v129, v0
	v_mov_b32_e32 v130, v0
	v_mov_b32_e32 v131, v0
	v_mov_b32_e32 v84, v0
	v_mov_b32_e32 v85, v0
	v_mov_b32_e32 v86, v0
	v_mov_b32_e32 v87, v0
	v_mov_b32_e32 v136, v0
	v_mov_b32_e32 v137, v0
	v_mov_b32_e32 v138, v0
	v_mov_b32_e32 v139, v0
	v_mov_b32_e32 v104, v0
	v_mov_b32_e32 v105, v0
	v_mov_b32_e32 v106, v0
	v_mov_b32_e32 v107, v0
	v_add_u32_e32 v154, 0x10000, v156
	ds_read_b128 v[92:95], v154
	ds_read_b128 v[96:99], v154 offset:1024
	ds_read_b128 v[172:175], v154 offset:2048
	ds_read_b128 v[176:179], v154 offset:3072
	ds_read_b128 v[180:183], v171
	ds_read_b128 v[204:207], v171 offset:1024
	ds_read_b128 v[208:211], v171 offset:2048
	ds_read_b128 v[212:215], v171 offset:3072
	ds_read_b128 v[216:219], v171 offset:4096
	ds_read_b128 v[220:223], v171 offset:5120
	ds_read_b128 v[224:227], v171 offset:6144
	ds_read_b128 v[228:231], v171 offset:7168
.LBB0_234:
	s_add_u32 s10, s38, vcc_lo
	s_addc_u32 s11, s39, vcc_hi
	s_add_u32 s16, s10, 0x100
	s_addc_u32 s17, s11, 0
	s_add_u32 s10, s10, 0x180
	s_addc_u32 s11, s11, 0
	s_add_u32 s14, s7, vcc_lo
	s_addc_u32 s15, s8, vcc_hi
	s_add_i32 s27, 0, 0x10000
	s_cmpk_eq_i32 vcc_lo, 0xf00
	s_cselect_b32 s15, s71, s15
	s_cselect_b32 s14, s70, s14
	s_cselect_b32 s21, s1, s17
	s_cselect_b32 s20, s0, s16
	s_cselect_b32 s17, s6, s11
	s_cselect_b32 s16, s3, s10
	v_lshl_add_u64 v[154:155], v[88:89], 0, vcc
	s_add_i32 m0, s91, 0xc000
	global_load_lds_dwordx4 v[154:155], off
	v_lshl_add_u64 v[154:155], v[90:91], 0, vcc
	s_add_i32 m0, s91, 0xe000
	s_nop 0
	global_load_lds_dwordx4 v[154:155], off
	s_waitcnt lgkmcnt(8)
	s_barrier
	s_waitcnt lgkmcnt(0)
	s_setprio 1
	s_waitcnt lgkmcnt(0)
	v_mfma_f32_16x16x32_bf16 v[104:107], v[92:95], v[180:183], v[104:107]
	v_mfma_f32_16x16x32_bf16 v[136:139], v[172:175], v[180:183], v[136:139]
	v_mfma_f32_16x16x32_bf16 v[84:87], v[92:95], v[208:211], v[84:87]
	v_mfma_f32_16x16x32_bf16 v[128:131], v[172:175], v[208:211], v[128:131]
	v_mfma_f32_16x16x32_bf16 v[76:79], v[92:95], v[216:219], v[76:79]
	v_mfma_f32_16x16x32_bf16 v[120:123], v[172:175], v[216:219], v[120:123]
	v_mfma_f32_16x16x32_bf16 v[68:71], v[92:95], v[224:227], v[68:71]
	v_mfma_f32_16x16x32_bf16 v[112:115], v[172:175], v[224:227], v[112:115]
	v_mfma_f32_16x16x32_bf16 v[104:107], v[96:99], v[204:207], v[104:107]
	v_mfma_f32_16x16x32_bf16 v[136:139], v[176:179], v[204:207], v[136:139]
	v_mfma_f32_16x16x32_bf16 v[84:87], v[96:99], v[212:215], v[84:87]
	v_mfma_f32_16x16x32_bf16 v[128:131], v[176:179], v[212:215], v[128:131]
	v_mfma_f32_16x16x32_bf16 v[76:79], v[96:99], v[220:223], v[76:79]
	v_mfma_f32_16x16x32_bf16 v[120:123], v[176:179], v[220:223], v[120:123]
	v_mfma_f32_16x16x32_bf16 v[68:71], v[96:99], v[228:231], v[68:71]
	v_mfma_f32_16x16x32_bf16 v[112:115], v[176:179], v[228:231], v[112:115]
	s_setprio 0
	s_barrier
; #define PG8_STAGE(bufoff, gbase, voff) do { _Pragma("unroll") for (int _i = 0; _i < 2; ++_i) \
;         __builtin_amdgcn_global_load_lds((const unsigned*)((const char*)(gbase) + (voff)[_i]), (LAS unsigned*)(lds + (bufoff) + ldsw + _i * 8192), 16, 0, 0); } while (0)
; #define PG8_STAGE_A(bufoff, ptr, half, rev) do { if (REVA && (rev)) { const char* _p = (ptr) - ((half) ? hstepA : 0); PG8_STAGE(bufoff, _p, voffAr); } else { const char* _p = (ptr) + ((half) ? hstepA : 0); PG8_STAGE(bufoff, _p, voffA); } } while (0)
; #define PG8_LDA(dst, b, h) do { _Pragma("unroll") for (int m = 0; m < 4; ++m) _Pragma("unroll") for (int k = 0; k < 2; ++k) dst[m][k] = *(const LAS bf16x8*)(lds + PG8_SA(b, h) + aoff + m * 2048 + k * 1024); } while (0)
; #define PG8_LDB(dst, b, h) do { _Pragma("unroll") for (int n = 0; n < 2; ++n) _Pragma("unroll") for (int k = 0; k < 2; ++k) dst[n][k] = *(const LAS bf16x8*)(lds + PG8_SB(b, h) + boff + n * 2048 + k * 1024); } while (0)
; #define PG8_MMA(ai, bj, At, Bt) do { __builtin_amdgcn_s_setprio(1); _Pragma("unroll") for (int m = 0; m < 4; ++m) _Pragma("unroll") for (int n = 0; n < 2; ++n) _Pragma("unroll") for (int k = 0; k < 2; ++k) \
;         acc[ai][bj][m][n] = __builtin_amdgcn_mfma_f32_16x16x32_bf16(Bt[n][k], At[m][k], acc[ai][bj][m][n], 0, 0, 0); __builtin_amdgcn_s_setprio(0); } while (0)
; #define PG8_WAIT_V(n) asm volatile("s_waitcnt vmcnt(" #n ")" ::: "memory")
; #define PG8_WAIT_L(n) asm volatile("s_waitcnt lgkmcnt(" #n ")" ::: "memory")
; #define PG8_BAR __builtin_amdgcn_s_barrier()
; #define PG8_SCHED __builtin_amdgcn_sched_barrier(0)
;     ...
;             PG8_LDB(B1, 0, 1); PG8_STAGE(PG8_SB(0, 0), b2, voffB);
;             PG8_BAR; PG8_WAIT_L(0); PG8_MMA(0, 1, At, B1); PG8_BAR;
;             PG8_LDA(At, 0, 1); PG8_STAGE_A(PG8_SA(0, 0), a2, 0, r2);
;             PG8_BAR; PG8_WAIT_L(0); PG8_MMA(1, 0, At, B0); PG8_BAR; PG8_SCHED;
;             PG8_STAGE(PG8_SB(0, 1), b2 + hb2, voffB);
;             PG8_WAIT_V(6); PG8_BAR; PG8_MMA(1, 1, At, B1); PG8_BAR;
;             PG8_LDB(B0, 1, 0); PG8_SCHED; PG8_LDA(At, 1, 0); PG8_STAGE_A(PG8_SA(0, 1), a2, 1, r2);
;             PG8_WAIT_L(8); PG8_BAR; PG8_WAIT_L(0); PG8_MMA(0, 0, At, B0); PG8_BAR; PG8_SCHED;
	s_add_i32 s37, 0, 0x14000
	v_add_u32_e32 v154, s37, v156
	s_add_i32 s10, s27, s90
	ds_read_b128 v[232:235], v154
	ds_read_b128 v[236:239], v154 offset:1024
	ds_read_b128 v[240:243], v154 offset:2048
	ds_read_b128 v[244:247], v154 offset:3072
	v_lshl_add_u64 v[154:155], s[14:15], 0, v[160:161]
	s_mov_b32 m0, s10
	v_lshl_add_u64 v[184:185], s[14:15], 0, v[140:141]
	global_load_lds_dwordx4 v[154:155], off
	s_add_i32 m0, s10, 0x2000
	s_nop 0
	global_load_lds_dwordx4 v[184:185], off
	s_barrier
	s_waitcnt lgkmcnt(0)
	s_setprio 1
	s_waitcnt lgkmcnt(0)
	v_mfma_f32_16x16x32_bf16 v[132:135], v[232:235], v[180:183], v[132:135]
	v_mfma_f32_16x16x32_bf16 v[100:103], v[240:243], v[180:183], v[100:103]
	ds_read_b128 v[180:183], v171 offset:16384
	v_mfma_f32_16x16x32_bf16 v[124:127], v[232:235], v[208:211], v[124:127]
	v_mfma_f32_16x16x32_bf16 v[80:83], v[240:243], v[208:211], v[80:83]
	ds_read_b128 v[208:211], v171 offset:18432
	v_mfma_f32_16x16x32_bf16 v[116:119], v[232:235], v[216:219], v[116:119]
	v_mfma_f32_16x16x32_bf16 v[72:75], v[240:243], v[216:219], v[72:75]
	ds_read_b128 v[216:219], v171 offset:20480
	v_mfma_f32_16x16x32_bf16 v[108:111], v[232:235], v[224:227], v[108:111]
	v_mfma_f32_16x16x32_bf16 v[64:67], v[240:243], v[224:227], v[64:67]
	ds_read_b128 v[224:227], v171 offset:22528
	v_mfma_f32_16x16x32_bf16 v[132:135], v[236:239], v[204:207], v[132:135]
	v_mfma_f32_16x16x32_bf16 v[100:103], v[244:247], v[204:207], v[100:103]
	ds_read_b128 v[204:207], v171 offset:17408
	v_mfma_f32_16x16x32_bf16 v[124:127], v[236:239], v[212:215], v[124:127]
	v_mfma_f32_16x16x32_bf16 v[80:83], v[244:247], v[212:215], v[80:83]
	ds_read_b128 v[212:215], v171 offset:19456
	v_mfma_f32_16x16x32_bf16 v[116:119], v[236:239], v[220:223], v[116:119]
	v_mfma_f32_16x16x32_bf16 v[72:75], v[244:247], v[220:223], v[72:75]
	ds_read_b128 v[220:223], v171 offset:21504
	v_mfma_f32_16x16x32_bf16 v[108:111], v[236:239], v[228:231], v[108:111]
	v_mfma_f32_16x16x32_bf16 v[64:67], v[244:247], v[228:231], v[64:67]
	ds_read_b128 v[228:231], v171 offset:23552
	s_setprio 0
	s_mov_b32 m0, s91
	v_lshl_add_u64 v[190:191], s[20:21], 0, v[160:161]
	s_barrier
	global_load_lds_dwordx4 v[190:191], off
	v_lshl_add_u64 v[190:191], s[20:21], 0, v[140:141]
	s_mov_b32 m0, s92
	s_nop 0
	global_load_lds_dwordx4 v[190:191], off
	s_waitcnt vmcnt(8)
	s_barrier
	s_waitcnt lgkmcnt(0)
	s_setprio 1
	s_waitcnt lgkmcnt(0)
	v_mfma_f32_16x16x32_bf16 v[28:31], v[92:95], v[180:183], v[28:31]
	v_mfma_f32_16x16x32_bf16 v[60:63], v[172:175], v[180:183], v[60:63]
	v_mfma_f32_16x16x32_bf16 v[20:23], v[92:95], v[208:211], v[20:23]
	v_mfma_f32_16x16x32_bf16 v[52:55], v[172:175], v[208:211], v[52:55]
	v_mfma_f32_16x16x32_bf16 v[12:15], v[92:95], v[216:219], v[12:15]
	v_mfma_f32_16x16x32_bf16 v[44:47], v[172:175], v[216:219], v[44:47]
	v_mfma_f32_16x16x32_bf16 v[4:7], v[92:95], v[224:227], v[4:7]
	v_mfma_f32_16x16x32_bf16 v[36:39], v[172:175], v[224:227], v[36:39]
	v_mfma_f32_16x16x32_bf16 v[28:31], v[96:99], v[204:207], v[28:31]
	v_mfma_f32_16x16x32_bf16 v[60:63], v[176:179], v[204:207], v[60:63]
	v_mfma_f32_16x16x32_bf16 v[20:23], v[96:99], v[212:215], v[20:23]
	v_mfma_f32_16x16x32_bf16 v[52:55], v[176:179], v[212:215], v[52:55]
	v_mfma_f32_16x16x32_bf16 v[12:15], v[96:99], v[220:223], v[12:15]
	v_mfma_f32_16x16x32_bf16 v[44:47], v[176:179], v[220:223], v[44:47]
	v_mfma_f32_16x16x32_bf16 v[4:7], v[96:99], v[228:231], v[4:7]
	v_mfma_f32_16x16x32_bf16 v[36:39], v[176:179], v[228:231], v[36:39]
	s_setprio 0
	s_barrier
	s_add_u32 s10, s14, 0x80000
	s_addc_u32 s11, s15, 0
	s_add_i32 s27, s37, s90
	v_lshl_add_u64 v[92:93], s[10:11], 0, v[160:161]
	s_mov_b32 m0, s27
	s_nop 0
	global_load_lds_dwordx4 v[92:93], off
	v_lshl_add_u64 v[92:93], s[10:11], 0, v[140:141]
	s_add_i32 m0, s27, 0x2000
	s_nop 0
	global_load_lds_dwordx4 v[92:93], off
	v_add_u32_e32 v176, 0x18000, v156
	ds_read_b128 v[92:95], v176
	ds_read_b128 v[96:99], v176 offset:1024
	ds_read_b128 v[172:175], v176 offset:2048
	ds_read_b128 v[176:179], v176 offset:3072
	s_waitcnt vmcnt(6)
	s_barrier
	s_setprio 1
	v_mfma_f32_16x16x32_bf16 v[56:59], v[232:235], v[180:183], v[56:59]
	v_mfma_f32_16x16x32_bf16 v[24:27], v[240:243], v[180:183], v[24:27]
	ds_read_b128 v[180:183], v171 offset:32768
	v_mfma_f32_16x16x32_bf16 v[48:51], v[232:235], v[208:211], v[48:51]
	v_mfma_f32_16x16x32_bf16 v[16:19], v[240:243], v[208:211], v[16:19]
	ds_read_b128 v[208:211], v171 offset:34816
	v_mfma_f32_16x16x32_bf16 v[40:43], v[232:235], v[216:219], v[40:43]
	v_mfma_f32_16x16x32_bf16 v[8:11], v[240:243], v[216:219], v[8:11]
	ds_read_b128 v[216:219], v171 offset:36864
	v_mfma_f32_16x16x32_bf16 v[32:35], v[232:235], v[224:227], v[32:35]
	v_mfma_f32_16x16x32_bf16 v[0:3], v[240:243], v[224:227], v[0:3]
	ds_read_b128 v[224:227], v171 offset:38912
	v_mfma_f32_16x16x32_bf16 v[56:59], v[236:239], v[204:207], v[56:59]
	v_mfma_f32_16x16x32_bf16 v[24:27], v[244:247], v[204:207], v[24:27]
	ds_read_b128 v[204:207], v171 offset:33792
	v_mfma_f32_16x16x32_bf16 v[48:51], v[236:239], v[212:215], v[48:51]
	v_mfma_f32_16x16x32_bf16 v[16:19], v[244:247], v[212:215], v[16:19]
	ds_read_b128 v[212:215], v171 offset:35840
	v_mfma_f32_16x16x32_bf16 v[40:43], v[236:239], v[220:223], v[40:43]
	v_mfma_f32_16x16x32_bf16 v[8:11], v[244:247], v[220:223], v[8:11]
	ds_read_b128 v[220:223], v171 offset:37888
	v_mfma_f32_16x16x32_bf16 v[32:35], v[236:239], v[228:231], v[32:35]
	v_mfma_f32_16x16x32_bf16 v[0:3], v[244:247], v[228:231], v[0:3]
	ds_read_b128 v[228:231], v171 offset:39936
	s_setprio 0
	s_add_i32 s27, 0, 0x18000
	s_barrier
; #define PG8_STAGE(bufoff, gbase, voff) do { _Pragma("unroll") for (int _i = 0; _i < 2; ++_i) \
;         __builtin_amdgcn_global_load_lds((const unsigned*)((const char*)(gbase) + (voff)[_i]), (LAS unsigned*)(lds + (bufoff) + ldsw + _i * 8192), 16, 0, 0); } while (0)
; #define PG8_STAGE_A(bufoff, ptr, half, rev) do { if (REVA && (rev)) { const char* _p = (ptr) - ((half) ? hstepA : 0); PG8_STAGE(bufoff, _p, voffAr); } else { const char* _p = (ptr) + ((half) ? hstepA : 0); PG8_STAGE(bufoff, _p, voffA); } } while (0)
; #define PG8_LDA(dst, b, h) do { _Pragma("unroll") for (int m = 0; m < 4; ++m) _Pragma("unroll") for (int k = 0; k < 2; ++k) dst[m][k] = *(const LAS bf16x8*)(lds + PG8_SA(b, h) + aoff + m * 2048 + k * 1024); } while (0)
; #define PG8_LDB(dst, b, h) do { _Pragma("unroll") for (int n = 0; n < 2; ++n) _Pragma("unroll") for (int k = 0; k < 2; ++k) dst[n][k] = *(const LAS bf16x8*)(lds + PG8_SB(b, h) + boff + n * 2048 + k * 1024); } while (0)
; #define PG8_MMA(ai, bj, At, Bt) do { __builtin_amdgcn_s_setprio(1); _Pragma("unroll") for (int m = 0; m < 4; ++m) _Pragma("unroll") for (int n = 0; n < 2; ++n) _Pragma("unroll") for (int k = 0; k < 2; ++k) \
;         acc[ai][bj][m][n] = __builtin_amdgcn_mfma_f32_16x16x32_bf16(Bt[n][k], At[m][k], acc[ai][bj][m][n], 0, 0, 0); __builtin_amdgcn_s_setprio(0); } while (0)
; #define PG8_WAIT_V(n) asm volatile("s_waitcnt vmcnt(" #n ")" ::: "memory")
; #define PG8_WAIT_L(n) asm volatile("s_waitcnt lgkmcnt(" #n ")" ::: "memory")
; #define PG8_BAR __builtin_amdgcn_s_barrier()
; #define PG8_SCHED __builtin_amdgcn_sched_barrier(0)
;     ...
;             PG8_WAIT_L(8); PG8_BAR; PG8_WAIT_L(0); PG8_MMA(0, 0, At, B0); PG8_BAR; PG8_SCHED;
;             PG8_LDB(B1, 1, 1); PG8_STAGE(PG8_SB(1, 0), b3, voffB);
;             PG8_BAR; PG8_WAIT_L(0); PG8_MMA(0, 1, At, B1); PG8_BAR;
;             PG8_LDA(At, 1, 1); PG8_STAGE_A(PG8_SA(1, 0), a3, 0, r3);
;             PG8_BAR; PG8_WAIT_L(0); PG8_MMA(1, 0, At, B0); PG8_BAR; PG8_SCHED;
;             PG8_STAGE(PG8_SB(1, 1), b3 + hb2, voffB);
;             PG8_WAIT_V(6); PG8_BAR; PG8_MMA(1, 1, At, B1); PG8_BAR;
	s_add_u32 s10, s20, 0x80000
	s_addc_u32 s11, s21, 0
	s_mov_b32 m0, s93
	v_lshl_add_u64 v[190:191], s[10:11], 0, v[160:161]
	global_load_lds_dwordx4 v[190:191], off
	v_lshl_add_u64 v[190:191], s[10:11], 0, v[140:141]
	s_mov_b32 m0, s94
	s_nop 0
	global_load_lds_dwordx4 v[190:191], off
	s_waitcnt lgkmcnt(8)
	s_barrier
	s_waitcnt lgkmcnt(0)
	s_setprio 1
	s_waitcnt lgkmcnt(0)
	v_mfma_f32_16x16x32_bf16 v[104:107], v[92:95], v[180:183], v[104:107]
	v_mfma_f32_16x16x32_bf16 v[136:139], v[172:175], v[180:183], v[136:139]
	v_mfma_f32_16x16x32_bf16 v[84:87], v[92:95], v[208:211], v[84:87]
	v_mfma_f32_16x16x32_bf16 v[128:131], v[172:175], v[208:211], v[128:131]
	v_mfma_f32_16x16x32_bf16 v[76:79], v[92:95], v[216:219], v[76:79]
	v_mfma_f32_16x16x32_bf16 v[120:123], v[172:175], v[216:219], v[120:123]
	v_mfma_f32_16x16x32_bf16 v[68:71], v[92:95], v[224:227], v[68:71]
	v_mfma_f32_16x16x32_bf16 v[112:115], v[172:175], v[224:227], v[112:115]
	v_mfma_f32_16x16x32_bf16 v[104:107], v[96:99], v[204:207], v[104:107]
	v_mfma_f32_16x16x32_bf16 v[136:139], v[176:179], v[204:207], v[136:139]
	v_mfma_f32_16x16x32_bf16 v[84:87], v[96:99], v[212:215], v[84:87]
	v_mfma_f32_16x16x32_bf16 v[128:131], v[176:179], v[212:215], v[128:131]
	v_mfma_f32_16x16x32_bf16 v[76:79], v[96:99], v[220:223], v[76:79]
	v_mfma_f32_16x16x32_bf16 v[120:123], v[176:179], v[220:223], v[120:123]
	v_mfma_f32_16x16x32_bf16 v[68:71], v[96:99], v[228:231], v[68:71]
	v_mfma_f32_16x16x32_bf16 v[112:115], v[176:179], v[228:231], v[112:115]
	s_setprio 0
	s_barrier
	s_add_i32 s20, 0, 0x1c000
	s_add_i32 s10, s27, s90
	v_add_u32_e32 v190, s20, v156
	v_lshl_add_u64 v[154:155], v[154:155], 0, s[28:29]
	s_mov_b32 m0, s10
	ds_read_b128 v[232:235], v190
	ds_read_b128 v[236:239], v190 offset:1024
	ds_read_b128 v[240:243], v190 offset:2048
	ds_read_b128 v[244:247], v190 offset:3072
	global_load_lds_dwordx4 v[154:155], off
	v_lshl_add_u64 v[154:155], v[184:185], 0, s[28:29]
	s_add_i32 m0, s10, 0x2000
	s_nop 0
	global_load_lds_dwordx4 v[154:155], off
	s_barrier
	s_waitcnt lgkmcnt(0)
	s_setprio 1
	s_waitcnt lgkmcnt(0)
	v_mfma_f32_16x16x32_bf16 v[132:135], v[232:235], v[180:183], v[132:135]
	v_mfma_f32_16x16x32_bf16 v[100:103], v[240:243], v[180:183], v[100:103]
	ds_read_b128 v[180:183], v171 offset:49152
	v_mfma_f32_16x16x32_bf16 v[124:127], v[232:235], v[208:211], v[124:127]
	v_mfma_f32_16x16x32_bf16 v[80:83], v[240:243], v[208:211], v[80:83]
	ds_read_b128 v[208:211], v171 offset:51200
	v_mfma_f32_16x16x32_bf16 v[116:119], v[232:235], v[216:219], v[116:119]
	v_mfma_f32_16x16x32_bf16 v[72:75], v[240:243], v[216:219], v[72:75]
	ds_read_b128 v[216:219], v171 offset:53248
	v_mfma_f32_16x16x32_bf16 v[108:111], v[232:235], v[224:227], v[108:111]
	v_mfma_f32_16x16x32_bf16 v[64:67], v[240:243], v[224:227], v[64:67]
	ds_read_b128 v[224:227], v171 offset:55296
	v_mfma_f32_16x16x32_bf16 v[132:135], v[236:239], v[204:207], v[132:135]
	v_mfma_f32_16x16x32_bf16 v[100:103], v[244:247], v[204:207], v[100:103]
	ds_read_b128 v[204:207], v171 offset:50176
	v_mfma_f32_16x16x32_bf16 v[124:127], v[236:239], v[212:215], v[124:127]
	v_mfma_f32_16x16x32_bf16 v[80:83], v[244:247], v[212:215], v[80:83]
	ds_read_b128 v[212:215], v171 offset:52224
	v_mfma_f32_16x16x32_bf16 v[116:119], v[236:239], v[220:223], v[116:119]
	v_mfma_f32_16x16x32_bf16 v[72:75], v[244:247], v[220:223], v[72:75]
	ds_read_b128 v[220:223], v171 offset:54272
	v_mfma_f32_16x16x32_bf16 v[108:111], v[236:239], v[228:231], v[108:111]
	v_mfma_f32_16x16x32_bf16 v[64:67], v[244:247], v[228:231], v[64:67]
	ds_read_b128 v[228:231], v171 offset:56320
	s_setprio 0
	s_mov_b32 m0, s95
	v_lshl_add_u64 v[154:155], s[16:17], 0, v[160:161]
	s_barrier
	global_load_lds_dwordx4 v[154:155], off
	v_lshl_add_u64 v[154:155], s[16:17], 0, v[140:141]
	s_mov_b32 m0, s96
	s_nop 0
	global_load_lds_dwordx4 v[154:155], off
	s_waitcnt vmcnt(8)
	s_barrier
	s_waitcnt lgkmcnt(0)
	s_setprio 1
	s_waitcnt lgkmcnt(0)
	v_mfma_f32_16x16x32_bf16 v[28:31], v[92:95], v[180:183], v[28:31]
	v_mfma_f32_16x16x32_bf16 v[60:63], v[172:175], v[180:183], v[60:63]
	v_mfma_f32_16x16x32_bf16 v[20:23], v[92:95], v[208:211], v[20:23]
	v_mfma_f32_16x16x32_bf16 v[52:55], v[172:175], v[208:211], v[52:55]
	v_mfma_f32_16x16x32_bf16 v[12:15], v[92:95], v[216:219], v[12:15]
	v_mfma_f32_16x16x32_bf16 v[44:47], v[172:175], v[216:219], v[44:47]
	v_mfma_f32_16x16x32_bf16 v[4:7], v[92:95], v[224:227], v[4:7]
	v_mfma_f32_16x16x32_bf16 v[36:39], v[172:175], v[224:227], v[36:39]
	v_mfma_f32_16x16x32_bf16 v[28:31], v[96:99], v[204:207], v[28:31]
	v_mfma_f32_16x16x32_bf16 v[60:63], v[176:179], v[204:207], v[60:63]
	v_mfma_f32_16x16x32_bf16 v[20:23], v[96:99], v[212:215], v[20:23]
	v_mfma_f32_16x16x32_bf16 v[52:55], v[176:179], v[212:215], v[52:55]
	v_mfma_f32_16x16x32_bf16 v[12:15], v[96:99], v[220:223], v[12:15]
	v_mfma_f32_16x16x32_bf16 v[44:47], v[176:179], v[220:223], v[44:47]
	v_mfma_f32_16x16x32_bf16 v[4:7], v[96:99], v[228:231], v[4:7]
	v_mfma_f32_16x16x32_bf16 v[36:39], v[176:179], v[228:231], v[36:39]
	s_setprio 0
	s_barrier
	s_add_u32 s10, s14, 0x80080
	s_addc_u32 s11, s15, 0
	s_add_i32 s14, s20, s90
	v_lshl_add_u64 v[92:93], s[10:11], 0, v[160:161]
	s_mov_b32 m0, s14
	s_nop 0
	global_load_lds_dwordx4 v[92:93], off
	v_lshl_add_u64 v[92:93], s[10:11], 0, v[140:141]
	s_add_i32 m0, s14, 0x2000
	s_nop 0
	global_load_lds_dwordx4 v[92:93], off
	v_add_u32_e32 v154, 0x10000, v156
	ds_read_b128 v[92:95], v154
	ds_read_b128 v[96:99], v154 offset:1024
	ds_read_b128 v[172:175], v154 offset:2048
	ds_read_b128 v[176:179], v154 offset:3072
	s_waitcnt vmcnt(6)
	s_barrier
; #define PG8_MMA(ai, bj, At, Bt) do { __builtin_amdgcn_s_setprio(1); _Pragma("unroll") for (int m = 0; m < 4; ++m) _Pragma("unroll") for (int n = 0; n < 2; ++n) _Pragma("unroll") for (int k = 0; k < 2; ++k) \
;         acc[ai][bj][m][n] = __builtin_amdgcn_mfma_f32_16x16x32_bf16(Bt[n][k], At[m][k], acc[ai][bj][m][n], 0, 0, 0); __builtin_amdgcn_s_setprio(0); } while (0)
; #define PG8_WAIT_V(n) asm volatile("s_waitcnt vmcnt(" #n ")" ::: "memory")
; #define PG8_BAR __builtin_amdgcn_s_barrier()
;     ...
;             PG8_WAIT_V(6); PG8_BAR; PG8_MMA(1, 1, At, B1); PG8_BAR;
;         }
;     __device__ __forceinline__ void operator()(const f32x4 (&acc)[2][2][4][2], const Unit& u, int wr, int wc, int fr, int fq, int lane) const {
;         const int ch = u.pn * 64 + wc * 16 + 4 * fq;
;         const f32x4 w0 = *(const f32x4*)(cw + ch), w1 = *(const f32x4*)(cw + 4096 + ch), w2 = *(const f32x4*)(cw + 8192 + ch);
; #pragma unroll
;         for (int ai = 0; ai < 2; ++ai) {
;             f32x4 z[4], up[4], dn[4];
; #pragma unroll
;             for (int m = 0; m < 4; ++m) {
;                 z[m] = acc[ai][0][m][1] * acc[ai][1][m][0];
; #pragma unroll
;                 for (int j = 0; j < 4; ++j) { up[m][j] = __int_as_float(__builtin_amdgcn_update_dpp(0, __float_as_int(z[m][j]), 0x121, 0xF, 0xF, false));
;                                               dn[m][j] = __int_as_float(__builtin_amdgcn_update_dpp(0, __float_as_int(z[m][j]), 0x12F, 0xF, 0xF, false)); }
;             }
;             u32x2 wv[4];
; #pragma unroll
;             for (int m = 0; m < 4; ++m) {
;                 f32x4 zp, zn;
; #pragma unroll
;                 for (int j = 0; j < 4; ++j) {
;                     zp[j] = (fr > 0) ? up[m][j] : (m > 0 ? up[m > 0 ? m - 1 : 0][j] : 0.f);
;                     zn[j] = (fr < 15) ? dn[m][j] : (m < 3 ? dn[m < 3 ? m + 1 : 3][j] : 0.f);
	s_setprio 1
	v_mfma_f32_16x16x32_bf16 v[56:59], v[232:235], v[180:183], v[56:59]
	v_mfma_f32_16x16x32_bf16 v[24:27], v[240:243], v[180:183], v[24:27]
	ds_read_b128 v[180:183], v171
	v_mfma_f32_16x16x32_bf16 v[48:51], v[232:235], v[208:211], v[48:51]
	v_mfma_f32_16x16x32_bf16 v[16:19], v[240:243], v[208:211], v[16:19]
	ds_read_b128 v[208:211], v171 offset:2048
	v_mfma_f32_16x16x32_bf16 v[40:43], v[232:235], v[216:219], v[40:43]
	v_mfma_f32_16x16x32_bf16 v[8:11], v[240:243], v[216:219], v[8:11]
	ds_read_b128 v[216:219], v171 offset:4096
	v_mfma_f32_16x16x32_bf16 v[32:35], v[232:235], v[224:227], v[32:35]
	v_mfma_f32_16x16x32_bf16 v[0:3], v[240:243], v[224:227], v[0:3]
	ds_read_b128 v[224:227], v171 offset:6144
	v_mfma_f32_16x16x32_bf16 v[56:59], v[236:239], v[204:207], v[56:59]
	v_mfma_f32_16x16x32_bf16 v[24:27], v[244:247], v[204:207], v[24:27]
	ds_read_b128 v[204:207], v171 offset:1024
	v_mfma_f32_16x16x32_bf16 v[48:51], v[236:239], v[212:215], v[48:51]
	v_mfma_f32_16x16x32_bf16 v[16:19], v[244:247], v[212:215], v[16:19]
	ds_read_b128 v[212:215], v171 offset:3072
	v_mfma_f32_16x16x32_bf16 v[40:43], v[236:239], v[220:223], v[40:43]
	v_mfma_f32_16x16x32_bf16 v[8:11], v[244:247], v[220:223], v[8:11]
	ds_read_b128 v[220:223], v171 offset:5120
	v_mfma_f32_16x16x32_bf16 v[32:35], v[236:239], v[228:231], v[32:35]
	v_mfma_f32_16x16x32_bf16 v[0:3], v[244:247], v[228:231], v[0:3]
	ds_read_b128 v[228:231], v171 offset:7168
	s_setprio 0
	s_add_i32 s9, s9, 2
	s_add_u32 vcc_lo, vcc_lo, 0x100
	s_addc_u32 vcc_hi, vcc_hi, 0
	s_cmp_gt_u32 s9, 29
	s_barrier
	s_cbranch_scc0 .LBB0_234
	s_waitcnt lgkmcnt(0)
	v_lshl_or_b32 v154, s5, 6, v158
	v_ashrrev_i32_e32 v155, 31, v154
	v_lshlrev_b64 v[92:93], 2, v[154:155]
	v_lshl_add_u64 v[88:89], v[142:143], 0, v[92:93]
	v_lshl_add_u64 v[90:91], v[144:145], 0, v[92:93]
	global_load_dwordx4 v[96:99], v[88:89], off
	s_nop 0
	global_load_dwordx4 v[88:91], v[90:91], off
	v_lshl_add_u64 v[92:93], v[146:147], 0, v[92:93]
	global_load_dwordx4 v[92:95], v[92:93], off
	v_pk_mul_f32 v[134:135], v[138:139], v[134:135]
	v_mov_b32_e32 v172, v161
	v_mov_b32_e32 v174, v161
	v_mov_b32_e32 v173, v161
	v_mov_b32_dpp v172, v134 row_ror:1 row_mask:0xf bank_mask:0xf
	v_mov_b32_dpp v174, v135 row_ror:1 row_mask:0xf bank_mask:0xf
	v_mov_b32_e32 v175, v161
	v_pk_mul_f32 v[126:127], v[130:131], v[126:127]
	v_mov_b32_e32 v177, v161
	v_mov_b32_e32 v179, v161
	v_pk_mul_f32 v[116:117], v[120:121], v[116:117]
	v_cndmask_b32_e64 v120, v172, 0, s[42:43]
	v_cndmask_b32_e64 v121, v174, 0, s[42:43]
	v_mov_b32_dpp v173, v134 row_ror:15 row_mask:0xf bank_mask:0xf
	v_mov_b32_dpp v175, v135 row_ror:15 row_mask:0xf bank_mask:0xf
	v_mov_b32_dpp v177, v126 row_ror:15 row_mask:0xf bank_mask:0xf
	v_mov_b32_dpp v179, v127 row_ror:15 row_mask:0xf bank_mask:0xf
	v_pk_mul_f32 v[132:133], v[136:137], v[132:133]
	v_mov_b32_e32 v136, v161
	v_mov_b32_e32 v138, v161
	v_pk_mul_f32 v[118:119], v[122:123], v[118:119]
	v_cndmask_b32_e64 v122, v173, v177, s[44:45]
	v_cndmask_b32_e64 v123, v175, v179, s[44:45]
	v_mov_b32_dpp v136, v132 row_ror:1 row_mask:0xf bank_mask:0xf
	v_mov_b32_dpp v138, v133 row_ror:1 row_mask:0xf bank_mask:0xf
	v_mov_b32_e32 v137, v161
	v_mov_b32_e32 v139, v161
	v_pk_mul_f32 v[124:125], v[128:129], v[124:125]
	v_mov_b32_e32 v129, v161
	v_mov_b32_e32 v131, v161
	v_pk_mul_f32 v[108:109], v[112:113], v[108:109]
	v_cndmask_b32_e64 v112, v136, 0, s[42:43]
	v_cndmask_b32_e64 v113, v138, 0, s[42:43]
	v_mov_b32_dpp v137, v132 row_ror:15 row_mask:0xf bank_mask:0xf
	v_mov_b32_dpp v139, v133 row_ror:15 row_mask:0xf bank_mask:0xf
	v_mov_b32_dpp v129, v124 row_ror:15 row_mask:0xf bank_mask:0xf
	v_mov_b32_dpp v131, v125 row_ror:15 row_mask:0xf bank_mask:0xf
	v_pk_mul_f32 v[110:111], v[114:115], v[110:111]
	v_cndmask_b32_e64 v114, v137, v129, s[44:45]
	v_cndmask_b32_e64 v115, v139, v131, s[44:45]
	v_mov_b32_e32 v176, v161
	v_mov_b32_e32 v178, v161
	v_mov_b32_e32 v185, v161
	v_mov_b32_dpp v176, v126 row_ror:1 row_mask:0xf bank_mask:0xf
	v_mov_b32_dpp v178, v127 row_ror:1 row_mask:0xf bank_mask:0xf
	v_mov_b32_e32 v191, v161
	v_mov_b32_dpp v185, v118 row_ror:15 row_mask:0xf bank_mask:0xf
	v_mov_b32_e32 v128, v161
	v_mov_b32_dpp v191, v119 row_ror:15 row_mask:0xf bank_mask:0xf
	v_mov_b32_e32 v130, v161
	v_mov_b32_dpp v128, v124 row_ror:1 row_mask:0xf bank_mask:0xf
	v_mov_b32_e32 v181, v161
	v_mov_b32_dpp v130, v125 row_ror:1 row_mask:0xf bank_mask:0xf
	v_mov_b32_e32 v183, v161
	v_mov_b32_dpp v181, v116 row_ror:15 row_mask:0xf bank_mask:0xf
	v_mov_b32_e32 v184, v161
	v_mov_b32_dpp v183, v117 row_ror:15 row_mask:0xf bank_mask:0xf
	v_mov_b32_e32 v190, v161
	v_mov_b32_dpp v184, v118 row_ror:1 row_mask:0xf bank_mask:0xf
	v_mov_b32_e32 v209, v161
	v_mov_b32_dpp v190, v119 row_ror:1 row_mask:0xf bank_mask:0xf
	v_mov_b32_e32 v211, v161
	v_mov_b32_dpp v209, v110 row_ror:15 row_mask:0xf bank_mask:0xf
	v_mov_b32_e32 v180, v161
	v_mov_b32_dpp v211, v111 row_ror:15 row_mask:0xf bank_mask:0xf
	v_mov_b32_e32 v182, v161
	v_mov_b32_dpp v180, v116 row_ror:1 row_mask:0xf bank_mask:0xf
	v_mov_b32_e32 v205, v161
	v_mov_b32_dpp v182, v117 row_ror:1 row_mask:0xf bank_mask:0xf
	v_mov_b32_e32 v207, v161
	v_mov_b32_dpp v205, v108 row_ror:15 row_mask:0xf bank_mask:0xf
	v_mov_b32_e32 v208, v161
	v_mov_b32_dpp v207, v109 row_ror:15 row_mask:0xf bank_mask:0xf
	v_mov_b32_e32 v210, v161
	v_mov_b32_dpp v208, v110 row_ror:1 row_mask:0xf bank_mask:0xf
	v_mov_b32_e32 v204, v161
	s_waitcnt vmcnt(0)
; __device__ __forceinline__ unsigned cvt_pk_bf16(float lo, float hi) { unsigned r; asm volatile("v_cvt_pk_bf16_f32 %0, %1, %2" : "=v"(r) : "v"(lo), "v"(hi)); return r; }
; __device__ __forceinline__ float silu_f(float x) { return x * __builtin_amdgcn_rcpf(1.f + __expf(-x)); }
;     __device__ __forceinline__ void operator()(const f32x4 (&acc)[2][2][4][2], const Unit& u, int wr, int wc, int fr, int fq, int lane) const {
;     ...
;             for (int m = 0; m < 4; ++m) {
;                 f32x4 zp, zn;
; #pragma unroll
;                 for (int j = 0; j < 4; ++j) {
;                     zp[j] = (fr > 0) ? up[m][j] : (m > 0 ? up[m > 0 ? m - 1 : 0][j] : 0.f);
;                     zn[j] = (fr < 15) ? dn[m][j] : (m < 3 ? dn[m < 3 ? m + 1 : 3][j] : 0.f);
;                 }
;                 f32x4 y = w0 * zp + w1 * z[m] + w2 * zn;
;                 const f32x4 bg = acc[ai][0][m][0], g = acc[ai][1][m][1];
; #pragma unroll
;                 for (int j = 0; j < 4; ++j) y[j] = y[j] * bg[j] * silu_f(g[j]);
;                 wv[m].x = cvt_pk_bf16(y[0], y[1]); wv[m].y = cvt_pk_bf16(y[2], y[3]);
;             }
;             if (u.pm < 128) {
	v_pk_mul_f32 v[120:121], v[98:99], v[120:121]
	v_pk_mul_f32 v[112:113], v[96:97], v[112:113]
	v_pk_fma_f32 v[120:121], v[134:135], v[90:91], v[120:121]
	v_mul_f32_e32 v134, 0xbfb8aa3b, v100
	v_exp_f32_e32 v134, v134
	v_pk_fma_f32 v[120:121], v[94:95], v[122:123], v[120:121]
	v_mov_b32_e32 v122, v100
	v_mul_f32_e32 v100, 0xbfb8aa3b, v101
	v_exp_f32_e32 v100, v100
	v_pk_fma_f32 v[112:113], v[132:133], v[88:89], v[112:113]
	v_mov_b32_e32 v123, v104
	v_pk_fma_f32 v[112:113], v[92:93], v[114:115], v[112:113]
	v_add_f32_e32 v114, 1.0, v134
	v_rcp_f32_e32 v114, v114
	v_add_f32_e32 v100, 1.0, v100
	v_mov_b32_e32 v115, v112
	v_rcp_f32_e32 v112, v100
	v_pk_mul_f32 v[114:115], v[122:123], v[114:115]
	v_mul_f32_e32 v100, 0xbfb8aa3b, v102
	v_mov_b32_e32 v104, v101
	v_mul_f32_e32 v114, v114, v115
	v_exp_f32_e32 v115, v100
	v_pk_mul_f32 v[100:101], v[104:105], v[112:113]
	v_mov_b32_e32 v104, v102
	v_mul_f32_e32 v112, v100, v101
	v_mul_f32_e32 v101, 0xbfb8aa3b, v103
	v_exp_f32_e32 v113, v101
	v_add_f32_e32 v100, 1.0, v115
	v_rcp_f32_e32 v100, v100
	v_mov_b32_e32 v101, v120
	v_add_f32_e32 v102, 1.0, v113
	v_rcp_f32_e32 v120, v102
	v_mov_b32_e32 v105, v106
	v_pk_mul_f32 v[100:101], v[104:105], v[100:101]
	v_mov_b32_e32 v106, v103
	v_mul_f32_e32 v102, v100, v101
	v_pk_mul_f32 v[100:101], v[106:107], v[120:121]
	v_cndmask_b32_e64 v106, v176, v172, s[42:43]
	v_cndmask_b32_e64 v107, v178, v174, s[42:43]
	v_pk_mul_f32 v[106:107], v[98:99], v[106:107]
	v_mul_f32_e32 v101, v100, v101
	v_cvt_pk_bf16_f32 v100, v114, v112
	v_cndmask_b32_e64 v112, v177, v185, s[44:45]
	v_cndmask_b32_e64 v113, v179, v191, s[44:45]
	v_pk_fma_f32 v[106:107], v[126:127], v[90:91], v[106:107]
	v_mul_f32_e32 v114, 0xbfb8aa3b, v80
	v_exp_f32_e32 v114, v114
	v_pk_fma_f32 v[106:107], v[94:95], v[112:113], v[106:107]
	v_mov_b32_e32 v112, v80
	v_mul_f32_e32 v80, 0xbfb8aa3b, v81
	v_cvt_pk_bf16_f32 v101, v102, v101
	v_cndmask_b32_e64 v102, v128, v136, s[42:43]
	v_cndmask_b32_e64 v103, v130, v138, s[42:43]
	v_exp_f32_e32 v80, v80
	v_pk_mul_f32 v[102:103], v[96:97], v[102:103]
	v_cndmask_b32_e64 v104, v129, v181, s[44:45]
	v_cndmask_b32_e64 v105, v131, v183, s[44:45]
	v_pk_fma_f32 v[102:103], v[124:125], v[88:89], v[102:103]
	v_add_f32_e32 v80, 1.0, v80
	v_pk_fma_f32 v[102:103], v[92:93], v[104:105], v[102:103]
	v_add_f32_e32 v104, 1.0, v114
	v_rcp_f32_e32 v104, v104
	v_mov_b32_e32 v105, v102
	v_rcp_f32_e32 v102, v80
	v_mov_b32_e32 v113, v84
	v_pk_mul_f32 v[104:105], v[112:113], v[104:105]
	v_mul_f32_e32 v80, 0xbfb8aa3b, v82
	v_mov_b32_e32 v84, v81
	v_mul_f32_e32 v104, v104, v105
	v_exp_f32_e32 v105, v80
	v_pk_mul_f32 v[80:81], v[84:85], v[102:103]
	v_mov_b32_e32 v84, v82
	v_mul_f32_e32 v102, v80, v81
	v_mul_f32_e32 v81, 0xbfb8aa3b, v83
	v_exp_f32_e32 v103, v81
	v_add_f32_e32 v80, 1.0, v105
	v_rcp_f32_e32 v80, v80
	v_mov_b32_e32 v81, v106
	v_add_f32_e32 v82, 1.0, v103
	v_rcp_f32_e32 v106, v82
	v_mov_b32_e32 v85, v86
	v_pk_mul_f32 v[80:81], v[84:85], v[80:81]
	v_mov_b32_e32 v86, v83
	v_mul_f32_e32 v82, v80, v81
	v_pk_mul_f32 v[80:81], v[86:87], v[106:107]
	v_cndmask_b32_e64 v86, v184, v176, s[42:43]
	v_cndmask_b32_e64 v87, v190, v178, s[42:43]
	v_pk_mul_f32 v[86:87], v[98:99], v[86:87]
	v_mul_f32_e32 v81, v80, v81
	v_cvt_pk_bf16_f32 v80, v104, v102
	v_cndmask_b32_e64 v102, v185, v209, s[44:45]
	v_cndmask_b32_e64 v103, v191, v211, s[44:45]
	v_pk_fma_f32 v[86:87], v[118:119], v[90:91], v[86:87]
	v_mul_f32_e32 v104, 0xbfb8aa3b, v72
	v_exp_f32_e32 v104, v104
	v_pk_fma_f32 v[86:87], v[94:95], v[102:103], v[86:87]
	v_mov_b32_e32 v102, v72
	v_mul_f32_e32 v72, 0xbfb8aa3b, v73
	v_cvt_pk_bf16_f32 v81, v82, v81
	v_cndmask_b32_e64 v82, v180, v128, s[42:43]
	v_cndmask_b32_e64 v83, v182, v130, s[42:43]
	v_exp_f32_e32 v72, v72
	v_pk_mul_f32 v[82:83], v[96:97], v[82:83]
	v_cndmask_b32_e64 v84, v181, v205, s[44:45]
	v_cndmask_b32_e64 v85, v183, v207, s[44:45]
	v_pk_fma_f32 v[82:83], v[116:117], v[88:89], v[82:83]
	v_add_f32_e32 v72, 1.0, v72
	v_pk_fma_f32 v[82:83], v[92:93], v[84:85], v[82:83]
	v_add_f32_e32 v84, 1.0, v104
	v_rcp_f32_e32 v84, v84
	v_mov_b32_e32 v85, v82
	v_rcp_f32_e32 v82, v72
	v_mov_b32_e32 v103, v76
	v_pk_mul_f32 v[84:85], v[102:103], v[84:85]
	v_mul_f32_e32 v72, 0xbfb8aa3b, v74
	v_mov_b32_e32 v76, v73
	v_mul_f32_e32 v84, v84, v85
	v_exp_f32_e32 v85, v72
	v_pk_mul_f32 v[72:73], v[76:77], v[82:83]
	v_mov_b32_e32 v76, v74
	v_mul_f32_e32 v82, v72, v73
	v_mul_f32_e32 v73, 0xbfb8aa3b, v75
	v_exp_f32_e32 v83, v73
	v_add_f32_e32 v72, 1.0, v85
	v_rcp_f32_e32 v72, v72
	v_mov_b32_e32 v73, v86
	v_add_f32_e32 v74, 1.0, v83
	v_rcp_f32_e32 v86, v74
	v_mov_b32_e32 v77, v78
	v_mov_b32_dpp v210, v111 row_ror:1 row_mask:0xf bank_mask:0xf
	v_pk_mul_f32 v[72:73], v[76:77], v[72:73]
	v_mov_b32_e32 v78, v75
	v_mul_f32_e32 v74, v72, v73
	v_pk_mul_f32 v[72:73], v[78:79], v[86:87]
	v_cndmask_b32_e64 v78, v208, v184, s[42:43]
	v_cndmask_b32_e64 v79, v210, v190, s[42:43]
	v_pk_mul_f32 v[78:79], v[98:99], v[78:79]
	v_mov_b32_e32 v206, v161
	v_mul_f32_e32 v73, v72, v73
	v_cvt_pk_bf16_f32 v72, v84, v82
	v_cndmask_b32_e64 v82, v209, 0, s[44:45]
	v_cndmask_b32_e64 v83, v211, 0, s[44:45]
	v_pk_fma_f32 v[78:79], v[110:111], v[90:91], v[78:79]
	v_mul_f32_e32 v84, 0xbfb8aa3b, v64
	v_mov_b32_dpp v204, v108 row_ror:1 row_mask:0xf bank_mask:0xf
	v_mov_b32_dpp v206, v109 row_ror:1 row_mask:0xf bank_mask:0xf
	v_exp_f32_e32 v84, v84
	v_pk_fma_f32 v[78:79], v[94:95], v[82:83], v[78:79]
	v_mov_b32_e32 v82, v64
	v_mul_f32_e32 v64, 0xbfb8aa3b, v65
	v_cvt_pk_bf16_f32 v73, v74, v73
	v_cndmask_b32_e64 v74, v204, v180, s[42:43]
	v_cndmask_b32_e64 v75, v206, v182, s[42:43]
	v_exp_f32_e32 v64, v64
	v_pk_mul_f32 v[74:75], v[96:97], v[74:75]
	v_cndmask_b32_e64 v76, v205, 0, s[44:45]
	v_cndmask_b32_e64 v77, v207, 0, s[44:45]
	v_pk_fma_f32 v[74:75], v[108:109], v[88:89], v[74:75]
	v_add_f32_e32 v64, 1.0, v64
	v_pk_fma_f32 v[74:75], v[92:93], v[76:77], v[74:75]
	v_add_f32_e32 v76, 1.0, v84
	v_rcp_f32_e32 v76, v76
	v_mov_b32_e32 v77, v74
	v_rcp_f32_e32 v74, v64
	v_mov_b32_e32 v83, v68
	v_pk_mul_f32 v[76:77], v[82:83], v[76:77]
	v_mul_f32_e32 v64, 0xbfb8aa3b, v66
	v_mov_b32_e32 v68, v65
	v_mul_f32_e32 v76, v76, v77
	v_exp_f32_e32 v77, v64
	v_pk_mul_f32 v[64:65], v[68:69], v[74:75]
	v_mov_b32_e32 v68, v66
	v_mul_f32_e32 v74, v64, v65
	v_mul_f32_e32 v65, 0xbfb8aa3b, v67
	v_exp_f32_e32 v75, v65
	v_add_f32_e32 v64, 1.0, v77
	v_rcp_f32_e32 v64, v64
	v_mov_b32_e32 v65, v78
	v_add_f32_e32 v66, 1.0, v75
	v_rcp_f32_e32 v78, v66
	s_cmpk_gt_i32 s36, 0x7f
	v_mov_b32_e32 v69, v70
	s_cselect_b64 s[38:39], -1, 0
	s_lshl_b32 s3, s36, 2
	v_pk_mul_f32 v[64:65], v[68:69], v[64:65]
	v_mov_b32_e32 v70, v67
	s_add_i32 s3, s4, s3
	v_mul_f32_e32 v68, v64, v65
	v_pk_mul_f32 v[64:65], v[70:71], v[78:79]
	s_and_b64 vcc, exec, s[38:39]
	v_mul_f32_e32 v64, v64, v65
	v_cvt_pk_bf16_f32 v66, v76, v74
	v_cvt_pk_bf16_f32 v67, v68, v64
	s_cbranch_vccz .LBB0_241
;     __device__ __forceinline__ void operator()(const f32x4 (&acc)[2][2][4][2], const Unit& u, int wr, int wc, int fr, int fq, int lane) const {
;     ...
;             } else {
;                 const int gidx = (u.pm - 128) * 4 + ai * 2 + wr, b = gidx / 5, g5 = gidx - b * 5, t0 = 62 * g5 - 1;
;                 bf16_t* p = O + ((size_t)(TL + b * 256 + t0 + fr)) * 4096 + ch;
; #pragma unroll
;                 for (int m = 0; m < 4; ++m) { const int i2 = m * 16 + fr; if (i2 >= 1 && i2 <= 62 && t0 + i2 < 256) *(u32x2*)(p + (size_t)(m * 16) * 4096) = wv[m]; }
;             }
	s_mul_hi_i32 s5, s3, 0x66666667
	s_lshr_b32 s6, s5, 31
	s_ashr_i32 s5, s5, 1
	s_add_i32 s6, s5, s6
	s_mul_i32 s5, s6, -5
	s_add_i32 s5, s5, s3
	s_mul_i32 s5, s5, 62
	s_lshl_b32 s6, s6, 8
	s_add_i32 s6, s5, s6
	v_add_u32_e32 v64, s6, v170
	v_ashrrev_i32_e32 v65, 31, v64
	v_lshlrev_b64 v[68:69], 13, v[64:65]
	v_lshl_add_u64 v[64:65], s[24:25], 0, v[68:69]
	v_cmp_le_i32_e32 vcc, s5, v157
	v_lshl_add_u64 v[64:65], v[154:155], 1, v[64:65]
	s_and_b64 s[6:7], s[46:47], vcc
	s_and_saveexec_b64 s[14:15], s[6:7]
	s_cbranch_execnz .LBB0_256
	s_or_b64 exec, exec, s[14:15]
	v_cmp_le_i32_e32 vcc, s5, v159
	s_and_saveexec_b64 s[14:15], vcc
	s_cbranch_execnz .LBB0_257
